# light barriers extended to ffn_in->ffn_out->w_in of layer 0 (cross-XCD data there now stored write-through)
# speedup vs baseline: 1.0577x; 1.0055x over previous
.Lxb_have_census:
	v_readlane_b32 s28, v253, 61
	v_readlane_b32 s29, v253, 62
	v_readlane_b32 s38, v254, 1
	v_readlane_b32 s39, v254, 2
	v_mov_b32_e32 v3, 1
	s_mul_i32 s2, s2, s37
	s_mul_i32 s3, s3, s37
	s_nop 4
	global_atomic_add v3, v201, v3, s[28:29] sc0
	buffer_inv sc1
	s_waitcnt vmcnt(0)
	v_readfirstlane_b32 s28, v3
	s_nop 3
	s_add_u32 s28, s28, 1
	s_cmp_eq_u32 s28, s2
	s_cbranch_scc0 .Lxb_poll
	s_cmp_eq_u32 s74, 7
	s_cbranch_scc1 .Lxb_maybe_light
	s_cmp_eq_u32 s74, 8
	s_cbranch_scc1 .Lxb_maybe_light
	s_cmp_eq_u32 s74, 6
	s_cbranch_scc1 .Lxb_maybe_light
	s_cmp_eq_u32 s74, 12
	s_cbranch_scc1 .Lxb_maybe_light
	s_cmp_eq_u32 s74, 13
	s_cbranch_scc1 .Lxb_maybe_light
	s_branch .Lxb_flush

.LBB0_166:
	ds_read2_b32 v[16:17], v37 offset1:65
	ds_read2_b32 v[18:19], v37 offset0:130 offset1:195
	v_add_u32_e32 v22, 0x400, v37
	ds_read2_b32 v[20:21], v22 offset0:4 offset1:69
	ds_read2_b32 v[22:23], v22 offset0:134 offset1:199
	v_readlane_b32 s40, v254, 48
	s_waitcnt lgkmcnt(0)
	v_cvt_pk_bf16_f32 v16, v16, v17
	v_cvt_pk_bf16_f32 v17, v18, v19
	v_cvt_pk_bf16_f32 v18, v20, v21
	v_add_u32_e32 v20, s0, v36
	v_ashrrev_i32_e32 v21, 31, v20
	v_lshlrev_b64 v[20:21], 11, v[20:21]
	v_readlane_b32 s41, v254, 49
	s_ashr_i32 s3, s2, 31
	s_lshl_b64 s[2:3], s[2:3], 1
	v_lshl_add_u64 v[20:21], s[40:41], 0, v[20:21]
	v_lshl_add_u64 v[20:21], v[20:21], 0, s[2:3]
	v_cvt_pk_bf16_f32 v19, v22, v23
	v_lshl_add_u64 v[20:21], v[20:21], 0, v[200:201]
	global_store_dwordx4 v[20:21], v[16:19], off sc1
	ds_read2_b32 v[16:17], v39 offset1:65
	ds_read2_b32 v[18:19], v39 offset0:130 offset1:195
	v_add_u32_e32 v22, 0x400, v39
	ds_read2_b32 v[20:21], v22 offset0:4 offset1:69
	ds_read2_b32 v[22:23], v22 offset0:134 offset1:199
	v_add_u32_e32 v24, s0, v38
	v_ashrrev_i32_e32 v25, 31, v24
	s_waitcnt lgkmcnt(3)
	v_cvt_pk_bf16_f32 v16, v16, v17
	s_waitcnt lgkmcnt(2)
	v_cvt_pk_bf16_f32 v17, v18, v19
	s_waitcnt lgkmcnt(1)
	v_cvt_pk_bf16_f32 v18, v20, v21
	v_lshlrev_b64 v[20:21], 11, v[24:25]
	v_lshl_add_u64 v[20:21], s[40:41], 0, v[20:21]
	v_lshl_add_u64 v[20:21], v[20:21], 0, s[2:3]
	s_waitcnt lgkmcnt(0)
	v_cvt_pk_bf16_f32 v19, v22, v23
	v_lshl_add_u64 v[20:21], v[20:21], 0, v[200:201]
	global_store_dwordx4 v[20:21], v[16:19], off sc1
	s_waitcnt lgkmcnt(0)
	s_barrier
	s_add_i32 s1, s1, s29
	s_and_b64 vcc, exec, s[36:37]
	s_mov_b32 s2, s33
	s_mov_b32 s0, s38
	s_waitcnt vmcnt(5)
	v_mov_b32_e32 v16, v0
	v_mov_b32_e32 v17, v1
	v_mov_b32_e32 v18, v2
	v_mov_b32_e32 v19, v3
	s_waitcnt vmcnt(4)
	v_mov_b32_e32 v20, v4
	v_mov_b32_e32 v21, v5
	v_mov_b32_e32 v22, v6
	v_mov_b32_e32 v23, v7
	s_waitcnt vmcnt(3)
	v_mov_b32_e32 v24, v8
	v_mov_b32_e32 v25, v9
	v_mov_b32_e32 v26, v10
	v_mov_b32_e32 v27, v11
	s_waitcnt vmcnt(2)
	v_mov_b32_e32 v28, v12
	v_mov_b32_e32 v29, v13
	v_mov_b32_e32 v30, v14
	v_mov_b32_e32 v31, v15
	s_cbranch_vccnz .LBB0_171

.Lbias_col0:
	v_lshlrev_b32_e32 v162, 2, v162
	v_add_u32_e32 v163, s46, v162
	v_add_u32_e32 v164, s46, v163
	v_add_u32_e32 v165, s46, v164
	v_add_u32_e32 v166, s46, v165
	v_and_b32_e32 v160, 15, v160
	v_cmp_eq_u32_e64 s[52:53], 0, v160
	s_nop 4
	s_and_b64 exec, exec, s[52:53]
	global_store_dword v162, v80, s[44:45] sc1
	global_store_dword v162, v88, s[44:45] offset:4 sc1
	global_store_dword v163, v81, s[44:45] sc1
	global_store_dword v163, v89, s[44:45] offset:4 sc1
	global_store_dword v164, v82, s[44:45] sc1
	global_store_dword v164, v90, s[44:45] offset:4 sc1
	global_store_dword v165, v83, s[44:45] sc1
	global_store_dword v165, v91, s[44:45] offset:4 sc1
	global_store_dword v166, v84, s[44:45] sc1
	global_store_dword v166, v92, s[44:45] offset:4 sc1
	s_mov_b64 exec, s[50:51]
	s_add_i32 s54, s54, s70
	s_cmp_lt_i32 s54, s55
	s_cbranch_scc1 .Lbias_again
	v_mul_u32_u24_e32 v0, 0xc0, v228
	ds_read_b128 v[128:131], v0 offset:0
	ds_read_b128 v[132:135], v0 offset:16
	ds_read_b128 v[136:139], v0 offset:32
	ds_read_b128 v[140:143], v0 offset:48
	ds_read_b128 v[144:147], v0 offset:64
	ds_read_b128 v[148:151], v0 offset:80
	ds_read_b128 v[152:155], v0 offset:96
	ds_read_b128 v[156:159], v0 offset:112
	ds_read_b128 v[160:163], v0 offset:128
	ds_read_b128 v[164:167], v0 offset:144
	ds_read_b128 v[168:171], v0 offset:160
	ds_read_b128 v[172:175], v0 offset:176
	s_mov_b32 s28, s49
	v_readlane_b32 s40, v255, 42
	v_readlane_b32 s41, v255, 43
	v_readlane_b32 s42, v255, 44
	v_readlane_b32 s43, v255, 45
	v_readlane_b32 s44, v255, 46
	v_readlane_b32 s45, v255, 47
	v_readlane_b32 s46, v255, 48
	v_readlane_b32 s47, v255, 49
	v_readlane_b32 s48, v255, 50
	v_readlane_b32 s49, v255, 51
	v_readlane_b32 s50, v255, 52
	v_readlane_b32 s51, v255, 53
	v_readlane_b32 s52, v255, 54
	v_readlane_b32 s53, v255, 55
	v_readlane_b32 s54, v255, 56
	v_readlane_b32 s55, v255, 57
	s_waitcnt lgkmcnt(0)
	s_nop 3
	s_cmp_eq_u32 s28, 1
	s_cbranch_scc1 .Lbias_ret1
	s_cmp_eq_u32 s28, 2
	s_cbranch_scc1 .Lbias_ret2
	s_branch .Lbias_ret3
